# phase0 x->bf16 row loop software-pipelined: next row's 4 loads in flight while the current row is reduced and stored (double register buffer)
# baseline (speedup 1.0000x reference)
; __device__ __forceinline__ unsigned cvt_pk_bf16(float lo, float hi) { unsigned r; asm volatile("v_cvt_pk_bf16_f32 %0, %1, %2" : "=v"(r) : "v"(lo), "v"(hi)); return r; }
; __device__ __forceinline__ void phase0(const Args& a, unsigned char* lds) {
;     ...
;     const int lane = threadIdx.x & 63, gw = blockIdx.x * 8 + (threadIdx.x >> 6), NGW = gridDim.x * 8;
;     const float* x = a.in[I_X]; bf16_t* XB = (bf16_t*)(ws + WS_XB);
;     float* ss0 = (float*)(ws + WS_SS0); float* ss1 = (float*)(ws + WS_SS1); float* ss2 = (float*)(ws + WS_SS2);
;     for (int row = gw; row < MROWS; row += NGW) {
;         const f32x4* xr = (const f32x4*)(x + (size_t)row * DM) + lane;
;         f32x4 v[4]; float s = 0.f;
; #pragma unroll
;         for (int j = 0; j < 4; ++j) { v[j] = xr[64 * j]; s += v[j][0] * v[j][0] + v[j][1] * v[j][1] + v[j][2] * v[j][2] + v[j][3] * v[j][3]; }
;         s = wave_sum(s);
;         if (lane == 0) { ss0[row] = s; ss1[row] = 0.f; ss2[row] = 0.f; }
;         unsigned long long* o8 = (unsigned long long*)(XB + (size_t)row * DM) + lane;
; #pragma unroll
;         for (int j = 0; j < 4; ++j) o8[64 * j] = (unsigned long long)cvt_pk_bf16(v[j][0], v[j][1]) | ((unsigned long long)cvt_pk_bf16(v[j][2], v[j][3]) << 32);
;     }
.LBB0_145:
	s_lshl_b32 s82, s2, 3
	v_add_u32_e32 v18, s82, v18
	s_mov_b32 s0, 0x10000
	v_cmp_gt_i32_e32 vcc, s0, v18
	v_mbcnt_lo_u32_b32 v157, -1, 0
	s_and_saveexec_b64 s[6:7], vcc
	s_mov_b32 s96, s85
	s_cbranch_execz .LBB0_150
	s_waitcnt vmcnt(7)
	v_mbcnt_hi_u32_b32 v2, -1, v157
	v_and_b32_e32 v1, 64, v2
	s_waitcnt vmcnt(6)
	v_add_u32_e32 v3, 64, v1
	v_xor_b32_e32 v1, 1, v2
	v_cmp_lt_i32_e32 vcc, v1, v3
	s_waitcnt vmcnt(5)
	v_xor_b32_e32 v4, 2, v2
	s_load_dword s0, s[4:5], 0x10
	s_load_dword s8, s[4:5], 0x0
	v_cndmask_b32_e32 v1, v2, v1, vcc
	v_cmp_lt_i32_e32 vcc, v4, v3
	v_ashrrev_i32_e32 v19, 31, v18
	s_waitcnt lgkmcnt(0)
	s_lshr_b32 s0, s0, 16
	v_cndmask_b32_e32 v4, v2, v4, vcc
	v_lshlrev_b32_e32 v26, 2, v4
	v_xor_b32_e32 v4, 4, v2
	v_cmp_lt_i32_e32 vcc, v4, v3
	s_cmp_lg_u32 s0, 0
	s_cselect_b64 s[0:1], -1, 0
	v_cndmask_b32_e32 v4, v2, v4, vcc
	v_lshlrev_b32_e32 v27, 2, v4
	v_xor_b32_e32 v4, 8, v2
	v_cmp_lt_i32_e32 vcc, v4, v3
	s_cmp_lg_u64 s[0:1], 0
	s_addc_u32 s0, s8, 0
	v_cndmask_b32_e32 v4, v2, v4, vcc
	v_lshlrev_b32_e32 v28, 2, v4
	v_xor_b32_e32 v4, 16, v2
	v_cmp_lt_i32_e32 vcc, v4, v3
	s_lshl_b32 s8, s0, 3
	s_ashr_i32 s9, s8, 31
	v_cndmask_b32_e32 v4, v2, v4, vcc
	v_lshlrev_b32_e32 v29, 2, v4
	v_xor_b32_e32 v4, 32, v2
	v_cmp_lt_i32_e32 vcc, v4, v3
	v_lshlrev_b64 v[22:23], 11, v[18:19]
	s_mov_b64 s[16:17], 0xc00
	v_cndmask_b32_e32 v2, v2, v4, vcc
	v_lshlrev_b32_e32 v30, 2, v2
	v_lshlrev_b64 v[2:3], 12, v[18:19]
	v_lshl_or_b32 v2, v164, 4, v2
	v_lshl_add_u64 v[2:3], s[12:13], 0, v[2:3]
	v_lshlrev_b32_e32 v1, 2, v1
	v_cmp_eq_u32_e64 s[0:1], 0, v164
	v_lshlrev_b64 v[20:21], 2, v[18:19]
	s_lshl_b64 s[10:11], s[8:9], 2
	v_lshl_or_b32 v22, v164, 3, v22
	s_lshl_b64 s[14:15], s[8:9], 11
	v_lshl_add_u64 v[24:25], v[2:3], 0, s[16:17]
	s_lshl_b64 s[16:17], s[8:9], 12
	s_mov_b64 s[18:19], 0
	v_mov_b32_e32 v19, 0
	s_mov_b32 s9, 0xffff
	global_load_dwordx4 v[14:17], v[24:25], off offset:-3072
	global_load_dwordx4 v[2:5], v[24:25], off offset:-2048
	global_load_dwordx4 v[6:9], v[24:25], off offset:-1024
	global_load_dwordx4 v[10:13], v[24:25], off
	s_waitcnt vmcnt(0)
	s_branch .LBB0_148
.LBB0_147:
	s_or_b64 exec, exec, s[20:21]
	s_waitcnt lgkmcnt(0)
	v_lshl_add_u64 v[32:33], s[70:71], 0, v[22:23]
	v_cvt_pk_bf16_f32 v48, v48, v49
	v_cvt_pk_bf16_f32 v49, v50, v51
	v_add_co_u32_e32 v50, vcc, 0x4000000, v32
	v_add_u32_e32 v18, s8, v18
	s_nop 0
	v_addc_co_u32_e32 v51, vcc, 0, v33, vcc
	global_store_dwordx2 v[50:51], v[48:49], off
	v_cvt_pk_bf16_f32 v36, v36, v37
	v_cvt_pk_bf16_f32 v37, v38, v39
	v_cmp_lt_i32_e32 vcc, s9, v18
	global_store_dwordx2 v[50:51], v[36:37], off offset:512
	v_cvt_pk_bf16_f32 v36, v40, v41
	v_cvt_pk_bf16_f32 v37, v42, v43
	v_lshl_add_u64 v[20:21], v[20:21], 0, s[10:11]
	v_lshl_add_u64 v[22:23], v[22:23], 0, s[14:15]
	s_or_b64 s[18:19], vcc, s[18:19]
	v_lshl_add_u64 v[24:25], v[24:25], 0, s[16:17]
	global_store_dwordx2 v[50:51], v[36:37], off offset:1024
	v_cvt_pk_bf16_f32 v36, v44, v45
	v_cvt_pk_bf16_f32 v37, v46, v47
	global_store_dwordx2 v[50:51], v[36:37], off offset:1536
	s_andn2_b64 exec, exec, s[18:19]
	s_cbranch_execz .LBB0_150
.LBB0_148:
	s_waitcnt vmcnt(7)
	v_mov_b32_e32 v36, v2
	v_mov_b32_e32 v37, v3
	v_mov_b32_e32 v38, v4
	v_mov_b32_e32 v39, v5
	v_mov_b32_e32 v40, v6
	v_mov_b32_e32 v41, v7
	v_mov_b32_e32 v42, v8
	v_mov_b32_e32 v43, v9
	v_mov_b32_e32 v44, v10
	v_mov_b32_e32 v45, v11
	v_mov_b32_e32 v46, v12
	v_mov_b32_e32 v47, v13
	v_mov_b32_e32 v48, v14
	v_mov_b32_e32 v49, v15
	v_mov_b32_e32 v50, v16
	v_mov_b32_e32 v51, v17
	v_add_u32_e32 v35, s8, v18
	v_cmp_ge_i32_e32 vcc, s9, v35
	s_and_saveexec_b64 s[22:23], vcc
	v_lshl_add_u64 v[32:33], v[24:25], 0, s[16:17]
	global_load_dwordx4 v[14:17], v[32:33], off offset:-3072
	global_load_dwordx4 v[2:5], v[32:33], off offset:-2048
	global_load_dwordx4 v[6:9], v[32:33], off offset:-1024
	global_load_dwordx4 v[10:13], v[32:33], off
	s_mov_b64 exec, s[22:23]
	v_mul_f32_e32 v31, v49, v49
	v_mul_f32_e32 v32, v37, v37
	v_mul_f32_e32 v33, v41, v41
	v_fmac_f32_e32 v31, v48, v48
	v_fmac_f32_e32 v32, v36, v36
	v_mul_f32_e32 v34, v45, v45
	v_fmac_f32_e32 v33, v40, v40
	v_fmac_f32_e32 v31, v50, v50
	v_fmac_f32_e32 v32, v38, v38
	v_fmac_f32_e32 v34, v44, v44
	v_fmac_f32_e32 v33, v42, v42
	v_fmac_f32_e32 v31, v51, v51
	v_fmac_f32_e32 v32, v39, v39
	v_fmac_f32_e32 v34, v46, v46
	v_fmac_f32_e32 v33, v43, v43
	v_add_f32_e32 v31, v31, v32
	v_add_f32_e32 v31, v31, v33
	v_fmac_f32_e32 v34, v47, v47
	v_add_f32_e32 v31, v31, v34
	ds_bpermute_b32 v32, v1, v31
	s_waitcnt lgkmcnt(0)
	v_add_f32_e32 v31, v31, v32
	ds_bpermute_b32 v32, v26, v31
	s_waitcnt lgkmcnt(0)
	v_add_f32_e32 v31, v31, v32
	ds_bpermute_b32 v32, v27, v31
	s_waitcnt lgkmcnt(0)
	v_add_f32_e32 v31, v31, v32
	ds_bpermute_b32 v32, v28, v31
	s_waitcnt lgkmcnt(0)
	v_add_f32_e32 v31, v31, v32
	ds_bpermute_b32 v32, v29, v31
	s_waitcnt lgkmcnt(0)
	v_add_f32_e32 v31, v31, v32
	ds_bpermute_b32 v32, v30, v31
	s_and_saveexec_b64 s[20:21], s[0:1]
	s_cbranch_execz .LBB0_147
	s_waitcnt lgkmcnt(0)
	v_add_f32_e32 v31, v31, v32
	v_lshl_add_u64 v[32:33], s[70:71], 0, v[20:21]
	v_add_co_u32_e32 v34, vcc, 0x40000, v32
	global_store_dword v[32:33], v31, off
	s_nop 0
	v_addc_co_u32_e32 v35, vcc, 0, v33, vcc
	v_add_co_u32_e32 v32, vcc, 0x80000, v32
	global_store_dword v[34:35], v19, off
	s_nop 0
	v_addc_co_u32_e32 v33, vcc, 0, v33, vcc
	global_store_dword v[32:33], v19, off
	s_branch .LBB0_147
